# placement: +16 bytes of padding after the attention loop
# baseline (speedup 1.0000x reference)
.Lat_pv_done:
	s_nop 7
	v_cvt_pk_bf16_f32 v22, v240, v240
	v_cvt_pk_bf16_f32 v23, v241, v241
	v_cvt_pk_bf16_f32 v24, v242, v242
	v_cvt_pk_bf16_f32 v25, v243, v243
	v_cvt_pk_bf16_f32 v26, v244, v244
	v_cvt_pk_bf16_f32 v27, v245, v245
	v_cvt_pk_bf16_f32 v28, v246, v246
	v_cvt_pk_bf16_f32 v29, v247, v247
	v_cvt_pk_bf16_f32 v134, v248, v248
	v_cvt_pk_bf16_f32 v135, v249, v249
	v_cvt_pk_bf16_f32 v136, v250, v250
	v_cvt_pk_bf16_f32 v137, v251, v251
	v_cvt_pk_bf16_f32 v138, v120, v120
	v_cvt_pk_bf16_f32 v139, v121, v121
	v_cvt_pk_bf16_f32 v150, v122, v122
	v_cvt_pk_bf16_f32 v151, v123, v123
	global_store_short v17, v22, s[20:21]
	global_store_short v17, v23, s[20:21] offset:2048
	global_store_short v18, v24, s[20:21]
	global_store_short v18, v25, s[20:21] offset:2048
	global_store_short v17, v26, s[20:21] offset:32
	global_store_short v17, v27, s[20:21] offset:2080
	global_store_short v18, v28, s[20:21] offset:32
	global_store_short v18, v29, s[20:21] offset:2080
	global_store_short v17, v134, s[20:21] offset:64
	global_store_short v17, v135, s[20:21] offset:2112
	global_store_short v18, v136, s[20:21] offset:64
	global_store_short v18, v137, s[20:21] offset:2112
	global_store_short v17, v138, s[20:21] offset:96
	global_store_short v17, v139, s[20:21] offset:2144
	global_store_short v18, v150, s[20:21] offset:96
	global_store_short v18, v151, s[20:21] offset:2144
	s_add_u32 s3, s3, s6
	s_cmp_lt_u32 s3, 0x2000
	s_cbranch_scc1 .Lat_loop
	v_and_b32_e32 v10, 15, v0
	s_add_u32 s74, s0, 0xd8
	s_addc_u32 s75, s1, 0
	v_mov_b64_e32 v[2:3], s[74:75]
	s_mov_b64 s[64:65], exec
	s_nop 0
	s_nop 0
	s_nop 0
	s_nop 0
